# hand-written P4 residual epilogue (4 row groups in flight), diff-attn producer-first order + counted LDS waits, MLA prio+prefetch
# speedup vs baseline: 1.0227x; 1.0145x over previous
; #define SBAR() __builtin_amdgcn_sched_barrier(0)
; __device__ __forceinline__ int crow(int r, int hi) { return (r & 3) + 8 * (r >> 2) + 4 * hi; }
; template <int NQK, int NREG>
; __device__ __forceinline__ void qkt(f32x16& p0, f32x16& p1, const char* Ks, const char* KRs, const bf16x8* qr, const char* qrl, int r32, int hi) {
;   p0 = f32x16{}; p1 = f32x16{};
; #pragma unroll
;   for (int d0 = 0; d0 < 8; ++d0) { const int cb = (d0 * 16 + hi * 8) * 2;
;     bf16x8 b0 = *reinterpret_cast<const bf16x8*>(Ks + KSWZ(r32, cb));
;     bf16x8 b1 = *reinterpret_cast<const bf16x8*>(Ks + KSWZ(32 + r32, cb));
;     bf16x8 qq; if (d0 < NREG) qq = qr[d0 < NREG ? d0 : 0]; else qq = *reinterpret_cast<const bf16x8*>(qrl + KRSWZ(r32, (d0 - 4) * 2 + hi));
;     p0 = __builtin_amdgcn_mfma_f32_32x32x16_bf16(b0, qq, p0, 0, 0, 0);
;     p1 = __builtin_amdgcn_mfma_f32_32x32x16_bf16(b1, qq, p1, 0, 0, 0); }
; __device__ __forceinline__ void attn_core_pair(f32x16 (&o)[4], const bf16_t* __restrict__ Qb, const bf16_t* __restrict__ Kh, const bf16_t* __restrict__ Vh, const int seq, const float C, const float thr_raw, char* lds) {
;     ...
;     if (j >= 1) {
;       const int pp = (j - 1) & 1;
;       if (__builtin_amdgcn_readfirstlane(fl_l[pp * 4 + rb]) != 0u) {
;         const float* al = ma + 256 + pp * 128 + rb * 32;
; #pragma unroll
;         for (int d = 0; d < 4; ++d)
; #pragma unroll
;           for (int r = 0; r < 16; ++r) o[d][r] *= al[crow(r, hi)]; }
;       if (role != pp) { pa0 = *(const bf16x8*)(P_l); pa1 = *(const bf16x8*)(P_l + 1024); pa2 = *(const bf16x8*)(P_l + 2048); pa3 = *(const bf16x8*)(P_l + 3072); }
;       pv_d0(o, vb0 + vprev * (2 * SHM_V), pa0, pa1, pa2, pa3);
;     }
;     if (j < NT && role == par) {
;       float m_reg = (j == 0) ? -1e30f : m_l[r32], l_reg = (j == 0) ? 0.f : l_l[r32], mn, al;
;       SBAR(); qkt<8, 8>(p0, p1, K_lds + kb * SHM_K, nullptr, qr, nullptr, r32, hi);
;       partialSM(p0, p1, m_reg, mn, al, C, thr_raw);
;       finishSM(p0, p1, al, l_reg, pa0, pa1, pa2, pa3); SBAR();
.LBB0_383:
	v_cmp_ne_u32_e32 vcc, s30, v157
	s_and_saveexec_b64 s[30:31], vcc
	s_cbranch_execz .Ldiff_cons
	ds_read_b128 v[240:243], v225
	ds_read_b128 v[244:247], v225 offset:1024
	ds_read_b128 v[248:251], v225 offset:2048
	ds_read_b128 v[252:255], v225 offset:3072
	ds_read_b32 v163, v203
	ds_read_b32 v169, v201
	v_add_u32_e32 v68, v205, v155
	ds_read_b128 v[64:67], v68
	ds_read_b128 v[68:71], v68 offset:8192
	v_add_u32_e32 v171, v206, v155
	ds_read_b128 v[228:231], v171
	ds_read_b128 v[232:235], v171 offset:8192
	v_add_u32_e32 v171, v207, v155
	s_waitcnt lgkmcnt(3)
	v_mfma_f32_32x32x16_bf16 v[80:95], v[64:67], v[124:127], 0
	s_waitcnt lgkmcnt(2)
	v_mfma_f32_32x32x16_bf16 v[64:79], v[68:71], v[124:127], 0
	s_waitcnt lgkmcnt(1)
	v_mfma_f32_32x32x16_bf16 v[80:95], v[228:231], v[120:123], v[80:95]
	s_waitcnt lgkmcnt(0)
	v_mfma_f32_32x32x16_bf16 v[64:79], v[232:235], v[120:123], v[64:79]
	ds_read_b128 v[228:231], v171
	ds_read_b128 v[232:235], v171 offset:8192
	v_add_u32_e32 v171, v208, v155
	s_waitcnt lgkmcnt(1)
	v_mfma_f32_32x32x16_bf16 v[80:95], v[228:231], v[116:119], v[80:95]
	s_waitcnt lgkmcnt(0)
	v_mfma_f32_32x32x16_bf16 v[64:79], v[232:235], v[116:119], v[64:79]
	ds_read_b128 v[228:231], v171
	ds_read_b128 v[232:235], v171 offset:8192
	v_add_u32_e32 v171, v209, v155
	s_waitcnt lgkmcnt(1)
	v_mfma_f32_32x32x16_bf16 v[80:95], v[228:231], v[112:115], v[80:95]
	s_waitcnt lgkmcnt(0)
	v_mfma_f32_32x32x16_bf16 v[64:79], v[232:235], v[112:115], v[64:79]
	ds_read_b128 v[228:231], v171
	ds_read_b128 v[232:235], v171 offset:8192
	v_add_u32_e32 v171, v210, v155
	s_waitcnt lgkmcnt(1)
	v_mfma_f32_32x32x16_bf16 v[80:95], v[228:231], v[108:111], v[80:95]
	s_waitcnt lgkmcnt(0)
	v_mfma_f32_32x32x16_bf16 v[64:79], v[232:235], v[108:111], v[64:79]
	ds_read_b128 v[228:231], v171
	ds_read_b128 v[232:235], v171 offset:8192
	v_add_u32_e32 v171, v211, v155
	s_waitcnt lgkmcnt(1)
	v_mfma_f32_32x32x16_bf16 v[80:95], v[228:231], v[104:107], v[80:95]
	s_waitcnt lgkmcnt(0)
	v_mfma_f32_32x32x16_bf16 v[64:79], v[232:235], v[104:107], v[64:79]
	ds_read_b128 v[228:231], v171
	ds_read_b128 v[232:235], v171 offset:8192
	v_add_u32_e32 v171, v212, v155
	s_waitcnt lgkmcnt(1)
	v_mfma_f32_32x32x16_bf16 v[80:95], v[228:231], v[100:103], v[80:95]
	ds_read_b128 v[228:231], v171
	ds_read_b128 v[236:239], v171 offset:8192
	s_waitcnt lgkmcnt(1)
	v_mfma_f32_32x32x16_bf16 v[80:95], v[228:231], v[96:99], v[80:95]
	v_mfma_f32_32x32x16_bf16 v[64:79], v[232:235], v[100:103], v[64:79]
	s_nop 10
	v_max_f32_e32 v171, v81, v81
	v_max_f32_e32 v173, v80, v80
	v_max_f32_e32 v171, v173, v171
	v_max3_f32 v171, v171, v82, v83
	v_max3_f32 v171, v171, v84, v85
	v_max3_f32 v171, v171, v86, v87
	v_max3_f32 v171, v171, v88, v89
	s_waitcnt lgkmcnt(0)
	v_mfma_f32_32x32x16_bf16 v[64:79], v[236:239], v[96:99], v[64:79]
	v_max3_f32 v171, v171, v90, v91
	v_max3_f32 v171, v171, v92, v93
	v_max3_f32 v171, v171, v94, v95
	s_nop 8
	v_max3_f32 v171, v171, v64, v65
	v_max3_f32 v171, v171, v66, v67
	v_max3_f32 v171, v171, v68, v69
	v_max3_f32 v171, v171, v70, v71
	v_max3_f32 v171, v171, v72, v73
	v_max3_f32 v171, v171, v74, v75
	v_max3_f32 v171, v171, v76, v77
	v_max3_f32 v171, v171, v78, v79
	v_mov_b32_e32 v173, v171
	s_nop 1
	v_permlane32_swap_b32_e32 v171, v173
	v_max_f32_e32 v173, v173, v173
	v_max_f32_e32 v171, v171, v171
	v_max_f32_e32 v171, v171, v173
	v_sub_f32_e32 v173, v171, v169
	v_cmp_ge_f32_e32 vcc, s47, v173
	v_max_f32_e32 v173, v169, v169
	v_max_f32_e32 v171, v173, v171
	v_sub_f32_e32 v173, v169, v171
	v_mul_f32_e32 v173, 0x3e0293ee, v173
	v_exp_f32_e32 v173, v173
	s_cmp_eq_u64 vcc, exec
	s_cselect_b64 vcc, -1, 0
	v_cndmask_b32_e32 v171, v171, v169, vcc
	v_cndmask_b32_e64 v169, v173, 1.0, vcc
	v_mul_f32_e32 v173, 0xbe0293ee, v171
	v_fmamk_f32 v80, v80, 0x3e0293ee, v173
	v_fmamk_f32 v81, v81, 0x3e0293ee, v173
	v_fmamk_f32 v82, v82, 0x3e0293ee, v173
	v_fmamk_f32 v83, v83, 0x3e0293ee, v173
	v_fmamk_f32 v84, v84, 0x3e0293ee, v173
	v_fmamk_f32 v85, v85, 0x3e0293ee, v173
	v_fmamk_f32 v86, v86, 0x3e0293ee, v173
	v_fmamk_f32 v87, v87, 0x3e0293ee, v173
	v_fmamk_f32 v88, v88, 0x3e0293ee, v173
	v_fmamk_f32 v89, v89, 0x3e0293ee, v173
	v_fmamk_f32 v90, v90, 0x3e0293ee, v173
	v_fmamk_f32 v91, v91, 0x3e0293ee, v173
	v_fmamk_f32 v92, v92, 0x3e0293ee, v173
	v_fmamk_f32 v93, v93, 0x3e0293ee, v173
	v_fmamk_f32 v94, v94, 0x3e0293ee, v173
	v_fmamk_f32 v95, v95, 0x3e0293ee, v173
	v_fmamk_f32 v64, v64, 0x3e0293ee, v173
	v_fmamk_f32 v65, v65, 0x3e0293ee, v173
	v_fmamk_f32 v66, v66, 0x3e0293ee, v173
	v_fmamk_f32 v67, v67, 0x3e0293ee, v173
	v_fmamk_f32 v68, v68, 0x3e0293ee, v173
	v_fmamk_f32 v69, v69, 0x3e0293ee, v173
	v_fmamk_f32 v70, v70, 0x3e0293ee, v173
	v_fmamk_f32 v71, v71, 0x3e0293ee, v173
	v_fmamk_f32 v72, v72, 0x3e0293ee, v173
	v_fmamk_f32 v73, v73, 0x3e0293ee, v173
	v_fmamk_f32 v74, v74, 0x3e0293ee, v173
	v_fmamk_f32 v75, v75, 0x3e0293ee, v173
	v_fmamk_f32 v76, v76, 0x3e0293ee, v173
	v_fmamk_f32 v77, v77, 0x3e0293ee, v173
	v_fmamk_f32 v78, v78, 0x3e0293ee, v173
	v_fmac_f32_e32 v173, 0x3e0293ee, v79
	v_exp_f32_e32 v79, v80
	v_exp_f32_e32 v175, v81
	v_exp_f32_e32 v82, v82
	v_exp_f32_e32 v83, v83
	v_exp_f32_e32 v84, v84
	v_exp_f32_e32 v183, v64
	v_add_f32_e32 v64, 0, v79
	v_exp_f32_e32 v85, v85
	v_add_f32_e32 v64, v175, v64
	v_exp_f32_e32 v86, v86
	v_add_f32_e32 v64, v82, v64
	v_exp_f32_e32 v87, v87
	v_add_f32_e32 v64, v83, v64
	v_exp_f32_e32 v88, v88
	v_add_f32_e32 v64, v84, v64
	v_exp_f32_e32 v89, v89
	v_add_f32_e32 v64, v85, v64
	v_exp_f32_e32 v90, v90
	v_add_f32_e32 v64, v86, v64
	v_exp_f32_e32 v91, v91
	v_add_f32_e32 v64, v87, v64
	v_exp_f32_e32 v92, v92
	v_add_f32_e32 v64, v88, v64
	v_exp_f32_e32 v93, v93
; #define SBAR() __builtin_amdgcn_sched_barrier(0)
; #define PWRITE(kb_, vi_) do { const int kc = sc * 2; *(bf16x8*)(K_lds + (kb_) * SHM_K + KSWZ(sr, kc)) = ks0; *(bf16x8*)(K_lds + (kb_) * SHM_K + KSWZ(32 + sr, kc)) = ks1; \
;     char* vq = V_lds + (vi_) * (2 * SHM_V); *(bf16x8*)(vq + vst0) = va0; *(bf16x8*)(vq + vst1) = va1; *(bf16x8*)(vq + SHM_V + vst0) = vb_0; *(bf16x8*)(vq + SHM_V + vst1) = vb_1; } while (0)
; __device__ __forceinline__ void finishSM(f32x16& p0, f32x16& p1, float alpha, float& l_reg, bf16x8& pa0, bf16x8& pa1, bf16x8& pa2, bf16x8& pa3) {
; #pragma unroll
;   for (int r = 0; r < 16; ++r) p1[r] = __builtin_amdgcn_exp2f(p1[r]);
;   float ps = 0;
; #pragma unroll
;   for (int r = 0; r < 16; ++r) ps += p0[r];
; #pragma unroll
;   for (int r = 0; r < 16; ++r) ps += p1[r];
;   { auto rr = __builtin_amdgcn_permlane32_swap(__float_as_uint(ps), __float_as_uint(ps), false, false);
;     ps = __uint_as_float(rr[0]) + __uint_as_float(rr[1]); }
;   l_reg = l_reg * alpha + ps;
;     ...
;   PK4(p0, 0, pa0); PK4(p0, 8, pa1); PK4(p1, 0, pa2); PK4(p1, 8, pa3);
;     ...
; }
; __device__ __forceinline__ void attn_core_pair(f32x16 (&o)[4], const bf16_t* __restrict__ Qb, const bf16_t* __restrict__ Kh, const bf16_t* __restrict__ Vh, const int seq, const float C, const float thr_raw, char* lds) {
;     ...
;       if (role != pp) { pa0 = *(const bf16x8*)(P_l); pa1 = *(const bf16x8*)(P_l + 1024); pa2 = *(const bf16x8*)(P_l + 2048); pa3 = *(const bf16x8*)(P_l + 3072); }
;       pv_d0(o, vb0 + vprev * (2 * SHM_V), pa0, pa1, pa2, pa3);
;     }
;     if (j < NT && role == par) {
;       float m_reg = (j == 0) ? -1e30f : m_l[r32], l_reg = (j == 0) ? 0.f : l_l[r32], mn, al;
;       SBAR(); qkt<8, 8>(p0, p1, K_lds + kb * SHM_K, nullptr, qr, nullptr, r32, hi);
;       partialSM(p0, p1, m_reg, mn, al, C, thr_raw);
;       finishSM(p0, p1, al, l_reg, pa0, pa1, pa2, pa3); SBAR();
;       *(bf16x8*)(P_l) = pa0; *(bf16x8*)(P_l + 1024) = pa1; *(bf16x8*)(P_l + 2048) = pa2; *(bf16x8*)(P_l + 3072) = pa3;
;       const bool anyr = __any(al < 1.f);
;       if (hi == 0) { m_l[r32] = m_reg; l_l[r32] = l_reg; ma[256 + par * 128 + rb * 32 + r32] = al; }
;       if (lane == 0) fl_l[par * 4 + rb] = anyr ? 1u : 0u;
;     }
;     if (j + 1 < NT) { PWRITE(kb ^ 1, vnext); if (j + 2 < NT) PLOAD((j + 2) * KVBLK); }
	v_add_f32_e32 v64, v89, v64
	v_exp_f32_e32 v94, v94
	v_add_f32_e32 v64, v90, v64
	v_exp_f32_e32 v95, v95
	v_add_f32_e32 v64, v91, v64
	v_add_f32_e32 v64, v92, v64
	v_exp_f32_e32 v185, v65
	v_add_f32_e32 v64, v93, v64
	v_exp_f32_e32 v227, v66
	v_add_f32_e32 v64, v94, v64
	v_exp_f32_e32 v228, v67
	v_add_f32_e32 v64, v95, v64
	v_exp_f32_e32 v229, v68
	v_add_f32_e32 v64, v183, v64
	v_exp_f32_e32 v230, v69
	v_add_f32_e32 v64, v185, v64
	v_exp_f32_e32 v231, v70
	v_add_f32_e32 v64, v227, v64
	v_exp_f32_e32 v232, v71
	v_add_f32_e32 v64, v228, v64
	v_exp_f32_e32 v72, v72
	v_add_f32_e32 v64, v229, v64
	v_exp_f32_e32 v73, v73
	v_add_f32_e32 v64, v230, v64
	v_exp_f32_e32 v74, v74
	v_add_f32_e32 v64, v231, v64
	v_exp_f32_e32 v75, v75
	v_add_f32_e32 v64, v232, v64
	v_exp_f32_e32 v233, v76
	v_add_f32_e32 v64, v72, v64
	v_exp_f32_e32 v234, v77
	v_add_f32_e32 v64, v73, v64
	v_exp_f32_e32 v235, v78
	v_add_f32_e32 v64, v74, v64
	v_exp_f32_e32 v173, v173
	v_add_f32_e32 v64, v75, v64
	v_add_f32_e32 v64, v233, v64
	v_add_f32_e32 v64, v234, v64
	v_add_f32_e32 v64, v235, v64
	v_add_f32_e32 v80, v173, v64
	v_mov_b32_e32 v81, v80
	v_cvt_pk_bf16_f32 v64, v79, v175
	v_cvt_pk_bf16_f32 v65, v82, v83
	v_cvt_pk_bf16_f32 v66, v84, v85
	v_cvt_pk_bf16_f32 v67, v86, v87
	v_cvt_pk_bf16_f32 v68, v88, v89
	v_cvt_pk_bf16_f32 v69, v90, v91
	v_cvt_pk_bf16_f32 v70, v92, v93
	v_cvt_pk_bf16_f32 v71, v94, v95
	v_cvt_pk_bf16_f32 v76, v183, v185
	v_cvt_pk_bf16_f32 v77, v227, v228
	v_cvt_pk_bf16_f32 v78, v229, v230
	v_cvt_pk_bf16_f32 v79, v231, v232
	v_cvt_pk_bf16_f32 v72, v72, v73
	v_cvt_pk_bf16_f32 v73, v74, v75
	v_cvt_pk_bf16_f32 v74, v233, v234
	v_cvt_pk_bf16_f32 v75, v235, v173
	s_nop 1
	v_permlane32_swap_b32_e32 v80, v81
	v_permlane32_swap_b32_e32 v64, v66
	v_permlane32_swap_b32_e32 v65, v67
	v_permlane32_swap_b32_e32 v68, v70
	v_permlane32_swap_b32_e32 v69, v71
	v_permlane32_swap_b32_e32 v76, v78
	v_permlane32_swap_b32_e32 v77, v79
	v_permlane32_swap_b32_e32 v72, v74
	v_permlane32_swap_b32_e32 v73, v75
	v_cmp_gt_f32_e32 vcc, 1.0, v169
	ds_write_b128 v225, v[64:67]
	ds_write_b128 v225, v[68:71] offset:1024
	ds_write_b128 v225, v[76:79] offset:2048
	ds_write_b128 v225, v[72:75] offset:3072
	s_and_saveexec_b64 s[38:39], s[2:3]
	s_cbranch_execz .LBB0_388
	v_add_f32_e32 v80, v80, v81
	v_fmac_f32_e32 v80, v163, v169
	ds_write_b32 v201, v171
	ds_write_b32 v203, v80
	v_add_u32_e32 v80, v201, v213
	ds_write_b32 v80, v169 offset:1024
.LBB0_388:
	s_or_b64 exec, exec, s[38:39]
	s_and_saveexec_b64 s[38:39], s[4:5]
	s_cmp_lg_u64 vcc, 0
	s_cselect_b64 s[58:59], -1, 0
	v_cndmask_b32_e64 v80, 0, 1, s[58:59]
	v_add_u32_e32 v81, v200, v214
	ds_write_b32 v81, v80
	s_or_b64 exec, exec, s[38:39]
	v_lshl_add_u32 v163, s16, 15, v204
	ds_read_b64_tr_b16 v[80:81], v163 offset:0
	ds_read_b64_tr_b16 v[82:83], v163 offset:0x800
	ds_read_b64_tr_b16 v[84:85], v163 offset:0x1000
	ds_read_b64_tr_b16 v[86:87], v163 offset:0x1800
	ds_read_b64_tr_b16 v[88:89], v163 offset:0x2000
	ds_read_b64_tr_b16 v[90:91], v163 offset:0x2800
	ds_read_b64_tr_b16 v[92:93], v163 offset:0x3000
	ds_read_b64_tr_b16 v[94:95], v163 offset:0x3800
	s_waitcnt lgkmcnt(6)
	v_mfma_f32_32x32x16_bf16 v[48:63], v[240:243], v[80:83], v[48:63]
	ds_read_b64_tr_b16 v[80:81], v163 offset:0x200
	ds_read_b64_tr_b16 v[82:83], v163 offset:0xa00
	s_waitcnt lgkmcnt(6)
	v_mfma_f32_32x32x16_bf16 v[48:63], v[244:247], v[84:87], v[48:63]
	ds_read_b64_tr_b16 v[84:85], v163 offset:0x1200
	ds_read_b64_tr_b16 v[86:87], v163 offset:0x1a00
	s_waitcnt lgkmcnt(6)
	v_mfma_f32_32x32x16_bf16 v[48:63], v[248:251], v[88:91], v[48:63]
	ds_read_b64_tr_b16 v[88:89], v163 offset:0x2200
	ds_read_b64_tr_b16 v[90:91], v163 offset:0x2a00
	ds_read_b64_tr_b16 v[228:229], v163 offset:0x3200
	ds_read_b64_tr_b16 v[230:231], v163 offset:0x3a00
	s_waitcnt lgkmcnt(8)
	v_mfma_f32_32x32x16_bf16 v[48:63], v[252:255], v[92:95], v[48:63]
	s_waitcnt lgkmcnt(6)
	v_mfma_f32_32x32x16_bf16 v[32:47], v[240:243], v[80:83], v[32:47]
	ds_read_b64_tr_b16 v[80:81], v163 offset:0x400
	ds_read_b64_tr_b16 v[82:83], v163 offset:0xc00
	s_waitcnt lgkmcnt(6)
	v_mfma_f32_32x32x16_bf16 v[32:47], v[244:247], v[84:87], v[32:47]
	ds_read_b64_tr_b16 v[84:85], v163 offset:0x1400
	ds_read_b64_tr_b16 v[86:87], v163 offset:0x1c00
	s_waitcnt lgkmcnt(6)
	v_mfma_f32_32x32x16_bf16 v[32:47], v[248:251], v[88:91], v[32:47]
	ds_read_b64_tr_b16 v[88:89], v163 offset:0x2400
	ds_read_b64_tr_b16 v[90:91], v163 offset:0x2c00
	ds_read_b64_tr_b16 v[92:93], v163 offset:0x3400
	ds_read_b64_tr_b16 v[94:95], v163 offset:0x3c00
	s_waitcnt lgkmcnt(8)
	v_mfma_f32_32x32x16_bf16 v[32:47], v[252:255], v[228:231], v[32:47]
	s_waitcnt lgkmcnt(6)
	v_mfma_f32_32x32x16_bf16 v[16:31], v[240:243], v[80:83], v[16:31]
	ds_read_b64_tr_b16 v[80:81], v163 offset:0x600
	ds_read_b64_tr_b16 v[82:83], v163 offset:0xe00
	s_waitcnt lgkmcnt(6)
	v_mfma_f32_32x32x16_bf16 v[16:31], v[244:247], v[84:87], v[16:31]
	ds_read_b64_tr_b16 v[84:85], v163 offset:0x1600
	ds_read_b64_tr_b16 v[86:87], v163 offset:0x1e00
	s_waitcnt lgkmcnt(6)
	v_mfma_f32_32x32x16_bf16 v[16:31], v[248:251], v[88:91], v[16:31]
	ds_read_b64_tr_b16 v[88:89], v163 offset:0x2600
	ds_read_b64_tr_b16 v[90:91], v163 offset:0x2e00
	ds_read_b64_tr_b16 v[228:229], v163 offset:0x3600
	ds_read_b64_tr_b16 v[230:231], v163 offset:0x3e00
	s_waitcnt lgkmcnt(8)
	v_mfma_f32_32x32x16_bf16 v[16:31], v[252:255], v[92:95], v[16:31]
	s_waitcnt lgkmcnt(6)
	v_mfma_f32_32x32x16_bf16 v[0:15], v[240:243], v[80:83], v[0:15]
	s_waitcnt lgkmcnt(4)
	v_mfma_f32_32x32x16_bf16 v[0:15], v[244:247], v[84:87], v[0:15]
	s_waitcnt lgkmcnt(2)
	v_mfma_f32_32x32x16_bf16 v[0:15], v[248:251], v[88:91], v[0:15]
	s_waitcnt lgkmcnt(0)
	v_mfma_f32_32x32x16_bf16 v[0:15], v[252:255], v[228:231], v[0:15]
	s_branch .LBB0_391
; #define SBAR() __builtin_amdgcn_sched_barrier(0)
; template <int D0> __device__ __forceinline__ void pv_one(f32x16& od, int vb, bf16x8 pa0, bf16x8 pa1, bf16x8 pa2, bf16x8 pa3) {
;   const s16x4 l0 = tr_read<v_rd_off(D0, 0, 0)>(vb), h0 = tr_read<v_rd_off(D0, 0, 1)>(vb), l1 = tr_read<v_rd_off(D0, 1, 0)>(vb), h1 = tr_read<v_rd_off(D0, 1, 1)>(vb);
;   const s16x4 l2 = tr_read<v_rd_off(D0, 2, 0)>(vb), h2 = tr_read<v_rd_off(D0, 2, 1)>(vb), l3 = tr_read<v_rd_off(D0, 3, 0)>(vb), h3 = tr_read<v_rd_off(D0, 3, 1)>(vb);
;   asm volatile("s_waitcnt lgkmcnt(0)" ::: "memory"); SBAR();
;     ...
;   od = __builtin_amdgcn_mfma_f32_32x32x16_bf16(pa0, PK(l0, h0), od, 0, 0, 0);
;   od = __builtin_amdgcn_mfma_f32_32x32x16_bf16(pa1, PK(l1, h1), od, 0, 0, 0);
;   od = __builtin_amdgcn_mfma_f32_32x32x16_bf16(pa2, PK(l2, h2), od, 0, 0, 0);
;   od = __builtin_amdgcn_mfma_f32_32x32x16_bf16(pa3, PK(l3, h3), od, 0, 0, 0);
;     ...
; }
; __device__ __forceinline__ void pv_d0(f32x16* o, int vb, bf16x8 pa0, bf16x8 pa1, bf16x8 pa2, bf16x8 pa3) {
;   pv_one<0>(o[0], vb, pa0, pa1, pa2, pa3); pv_one<1>(o[1], vb, pa0, pa1, pa2, pa3); pv_one<2>(o[2], vb, pa0, pa1, pa2, pa3); pv_one<3>(o[3], vb, pa0, pa1, pa2, pa3);
; __device__ __forceinline__ void attn_core_pair(f32x16 (&o)[4], const bf16_t* __restrict__ Qb, const bf16_t* __restrict__ Kh, const bf16_t* __restrict__ Vh, const int seq, const float C, const float thr_raw, char* lds) {
;     ...
;       if (role != pp) { pa0 = *(const bf16x8*)(P_l); pa1 = *(const bf16x8*)(P_l + 1024); pa2 = *(const bf16x8*)(P_l + 2048); pa3 = *(const bf16x8*)(P_l + 3072); }
;       pv_d0(o, vb0 + vprev * (2 * SHM_V), pa0, pa1, pa2, pa3);
.Ldiff_cons:
	s_or_b64 exec, exec, s[30:31]
	v_lshl_add_u32 v163, s16, 15, v204
	ds_read_b64_tr_b16 v[80:81], v163 offset:0
	ds_read_b64_tr_b16 v[82:83], v163 offset:0x800
	ds_read_b64_tr_b16 v[84:85], v163 offset:0x1000
	ds_read_b64_tr_b16 v[86:87], v163 offset:0x1800
	ds_read_b64_tr_b16 v[88:89], v163 offset:0x2000
	ds_read_b64_tr_b16 v[90:91], v163 offset:0x2800
	ds_read_b64_tr_b16 v[92:93], v163 offset:0x3000
	ds_read_b64_tr_b16 v[94:95], v163 offset:0x3800
	s_waitcnt lgkmcnt(6)
	v_mfma_f32_32x32x16_bf16 v[48:63], v[64:67], v[80:83], v[48:63]
	ds_read_b64_tr_b16 v[80:81], v163 offset:0x200
	ds_read_b64_tr_b16 v[82:83], v163 offset:0xa00
	s_waitcnt lgkmcnt(6)
	v_mfma_f32_32x32x16_bf16 v[48:63], v[68:71], v[84:87], v[48:63]
	ds_read_b64_tr_b16 v[84:85], v163 offset:0x1200
	ds_read_b64_tr_b16 v[86:87], v163 offset:0x1a00
	s_waitcnt lgkmcnt(6)
	v_mfma_f32_32x32x16_bf16 v[48:63], v[76:79], v[88:91], v[48:63]
	ds_read_b64_tr_b16 v[88:89], v163 offset:0x2200
	ds_read_b64_tr_b16 v[90:91], v163 offset:0x2a00
	ds_read_b64_tr_b16 v[228:229], v163 offset:0x3200
	ds_read_b64_tr_b16 v[230:231], v163 offset:0x3a00
	s_waitcnt lgkmcnt(8)
	v_mfma_f32_32x32x16_bf16 v[48:63], v[72:75], v[92:95], v[48:63]
	s_waitcnt lgkmcnt(6)
	v_mfma_f32_32x32x16_bf16 v[32:47], v[64:67], v[80:83], v[32:47]
	ds_read_b64_tr_b16 v[80:81], v163 offset:0x400
	ds_read_b64_tr_b16 v[82:83], v163 offset:0xc00
	s_waitcnt lgkmcnt(6)
	v_mfma_f32_32x32x16_bf16 v[32:47], v[68:71], v[84:87], v[32:47]
	ds_read_b64_tr_b16 v[84:85], v163 offset:0x1400
	ds_read_b64_tr_b16 v[86:87], v163 offset:0x1c00
	s_waitcnt lgkmcnt(6)
	v_mfma_f32_32x32x16_bf16 v[32:47], v[76:79], v[88:91], v[32:47]
	ds_read_b64_tr_b16 v[88:89], v163 offset:0x2400
	ds_read_b64_tr_b16 v[90:91], v163 offset:0x2c00
	ds_read_b64_tr_b16 v[92:93], v163 offset:0x3400
	ds_read_b64_tr_b16 v[94:95], v163 offset:0x3c00
	s_waitcnt lgkmcnt(8)
	v_mfma_f32_32x32x16_bf16 v[32:47], v[72:75], v[228:231], v[32:47]
	s_waitcnt lgkmcnt(6)
	v_mfma_f32_32x32x16_bf16 v[16:31], v[64:67], v[80:83], v[16:31]
	ds_read_b64_tr_b16 v[80:81], v163 offset:0x600
	ds_read_b64_tr_b16 v[82:83], v163 offset:0xe00
	s_waitcnt lgkmcnt(6)
	v_mfma_f32_32x32x16_bf16 v[16:31], v[68:71], v[84:87], v[16:31]
	ds_read_b64_tr_b16 v[84:85], v163 offset:0x1600
	ds_read_b64_tr_b16 v[86:87], v163 offset:0x1e00
	s_waitcnt lgkmcnt(6)
	v_mfma_f32_32x32x16_bf16 v[16:31], v[76:79], v[88:91], v[16:31]
	ds_read_b64_tr_b16 v[88:89], v163 offset:0x2600
	ds_read_b64_tr_b16 v[90:91], v163 offset:0x2e00
	ds_read_b64_tr_b16 v[228:229], v163 offset:0x3600
	ds_read_b64_tr_b16 v[230:231], v163 offset:0x3e00
	s_waitcnt lgkmcnt(8)
	v_mfma_f32_32x32x16_bf16 v[16:31], v[72:75], v[92:95], v[16:31]
	s_waitcnt lgkmcnt(6)
	v_mfma_f32_32x32x16_bf16 v[0:15], v[64:67], v[80:83], v[0:15]
	s_waitcnt lgkmcnt(4)
	v_mfma_f32_32x32x16_bf16 v[0:15], v[68:71], v[84:87], v[0:15]
	s_waitcnt lgkmcnt(2)
	v_mfma_f32_32x32x16_bf16 v[0:15], v[76:79], v[88:91], v[0:15]
	s_waitcnt lgkmcnt(0)
	v_mfma_f32_32x32x16_bf16 v[0:15], v[72:75], v[228:231], v[0:15]

; #define EPI_FENCE() asm volatile("" ::: "memory")
; __device__ __forceinline__ u32x4 pack8(f32x4 a, f32x4 b) { u32x4 w; w.x = cvt_pk_bf16(a[0], a[1]); w.y = cvt_pk_bf16(a[2], a[3]); w.z = cvt_pk_bf16(b[0], b[1]); w.w = cvt_pk_bf16(b[2], b[3]); return w; }
; __device__ __forceinline__ float dot4(f32x4 a) { return (a[0] * a[0] + a[1] * a[1]) + (a[2] * a[2] + a[3] * a[3]); }
;   __device__ __forceinline__ void operator()(const AccT& acc, const pg8::Unit& u, int wr, int wc, int fr, int fq) const {
;     const int row0 = u.pm * 256 + wr * 64 + fr, col0 = u.pn * 256 + wc * 32 + 8 * fq;
; #pragma unroll
;     for (int ai = 0; ai < 2; ++ai)
; #pragma unroll
;       for (int m = 0; m < 4; ++m) { const int row = row0 + ai * 128 + m * 16; const size_t off = (size_t)row * DM + col0; float s = 0.f;
; #pragma unroll
;         for (int bj = 0; bj < 2; ++bj) { const int co = bj * 128;
;           const f32x4 v0 = *(const f32x4*)(base + off + co) + acc[ai][bj][m][0], v1 = *(const f32x4*)(base + off + co + 4) + acc[ai][bj][m][1];
;           *(f32x4*)(X + off + co) = v0; *(f32x4*)(X + off + co + 4) = v1; s += dot4(v0) + dot4(v1);
;           if (xb) { const f32x4 g0 = *(const f32x4*)(g + col0 + co), g1 = *(const f32x4*)(g + col0 + co + 4); *(u32x4*)(xb + off + co) = pack8(v0 * g0, v1 * g1); } }
;         s += __shfl_xor(s, 16); s += __shfl_xor(s, 32);
;         if (fq == 0) unsafeAtomicAdd(ss + row, s);
;         if (m & 1) EPI_FENCE(); }
;   }
.LBB0_516:
	v_lshl_add_u32 v149, s60, 8, v150
	v_lshl_or_b32 v252, s61, 8, v155
	v_lshlrev_b32_e32 v252, 2, v252
	v_lshl_add_u32 v148, v149, 13, v252
	v_lshlrev_b32_e32 v149, 2, v149
	global_load_dwordx4 v[144:147], v252, s[66:67]
	global_load_dwordx4 v[160:163], v252, s[66:67] offset:16
	global_load_dwordx4 v[164:167], v252, s[66:67] offset:512
	global_load_dwordx4 v[168:171], v252, s[66:67] offset:528
	v_xor_b32_e32 v254, 16, v159
	v_xor_b32_e32 v255, 32, v159
	v_lshlrev_b32_e32 v254, 2, v254
	v_lshlrev_b32_e32 v255, 2, v255
	global_load_dwordx4 v[172:175], v148, s[36:37]
	global_load_dwordx4 v[176:179], v148, s[36:37] offset:16
	global_load_dwordx4 v[180:183], v148, s[36:37] offset:512
	global_load_dwordx4 v[188:191], v148, s[36:37] offset:528
	v_add_u32_e32 v253, 0x20000, v148
	global_load_dwordx4 v[194:197], v253, s[36:37]
	global_load_dwordx4 v[198:201], v253, s[36:37] offset:16
	global_load_dwordx4 v[202:205], v253, s[36:37] offset:512
	global_load_dwordx4 v[206:209], v253, s[36:37] offset:528
	v_add_u32_e32 v253, 0x40000, v148
	global_load_dwordx4 v[210:213], v253, s[36:37]
	global_load_dwordx4 v[214:217], v253, s[36:37] offset:16
	global_load_dwordx4 v[218:221], v253, s[36:37] offset:512
	global_load_dwordx4 v[222:225], v253, s[36:37] offset:528
	v_add_u32_e32 v253, 0x60000, v148
	global_load_dwordx4 v[234:237], v253, s[36:37]
	global_load_dwordx4 v[238:241], v253, s[36:37] offset:16
	global_load_dwordx4 v[242:245], v253, s[36:37] offset:512
	global_load_dwordx4 v[246:249], v253, s[36:37] offset:528
	s_waitcnt vmcnt(12)
	v_pk_add_f32 v[120:121], v[120:121], v[172:173]
	v_pk_add_f32 v[122:123], v[122:123], v[174:175]
	v_pk_add_f32 v[124:125], v[124:125], v[176:177]
	v_pk_add_f32 v[126:127], v[126:127], v[178:179]
	v_pk_add_f32 v[116:117], v[116:117], v[180:181]
	v_pk_add_f32 v[118:119], v[118:119], v[182:183]
	v_pk_add_f32 v[112:113], v[112:113], v[188:189]
	v_pk_add_f32 v[114:115], v[114:115], v[190:191]
	global_store_dwordx4 v148, v[120:123], s[72:73]
	global_store_dwordx4 v148, v[124:127], s[72:73] offset:16
	global_store_dwordx4 v148, v[116:119], s[72:73] offset:512
	global_store_dwordx4 v148, v[112:115], s[72:73] offset:528
	v_mul_f32_e32 v250, v120, v120
	v_mul_f32_e32 v251, v121, v121
	v_fmac_f32_e32 v250, v122, v122
	v_fmac_f32_e32 v251, v123, v123
	v_fmac_f32_e32 v250, v124, v124
	v_fmac_f32_e32 v251, v125, v125
	v_fmac_f32_e32 v250, v126, v126
	v_fmac_f32_e32 v251, v127, v127
	v_fmac_f32_e32 v250, v116, v116
	v_fmac_f32_e32 v251, v117, v117
	v_fmac_f32_e32 v250, v118, v118
	v_fmac_f32_e32 v251, v119, v119
	v_fmac_f32_e32 v250, v112, v112
	v_fmac_f32_e32 v251, v113, v113
	v_fmac_f32_e32 v250, v114, v114
	v_fmac_f32_e32 v251, v115, v115
	v_add_f32_e32 v250, v250, v251
	ds_bpermute_b32 v251, v254, v250
	v_pk_mul_f32 v[172:173], v[120:121], v[144:145]
	v_pk_mul_f32 v[174:175], v[122:123], v[146:147]
	v_pk_mul_f32 v[176:177], v[124:125], v[160:161]
	v_pk_mul_f32 v[178:179], v[126:127], v[162:163]
	v_pk_mul_f32 v[180:181], v[116:117], v[164:165]
	v_pk_mul_f32 v[182:183], v[118:119], v[166:167]
	v_pk_mul_f32 v[188:189], v[112:113], v[168:169]
	v_pk_mul_f32 v[190:191], v[114:115], v[170:171]
	v_cvt_pk_bf16_f32 v172, v172, v173
	v_cvt_pk_bf16_f32 v173, v174, v175
	v_cvt_pk_bf16_f32 v174, v176, v177
	v_cvt_pk_bf16_f32 v175, v178, v179
	v_cvt_pk_bf16_f32 v180, v180, v181
	v_cvt_pk_bf16_f32 v181, v182, v183
	v_cvt_pk_bf16_f32 v182, v188, v189
	v_cvt_pk_bf16_f32 v183, v190, v191
	v_lshrrev_b32_e32 v252, 1, v148
	global_store_dwordx4 v252, v[172:175], s[16:17]
	global_store_dwordx4 v252, v[180:183], s[16:17] offset:256
	s_waitcnt lgkmcnt(0)
	v_add_f32_e32 v250, v250, v251
	ds_bpermute_b32 v251, v255, v250
	s_nop 0
	v_add_u32_e32 v253, 0x100000, v148
	global_load_dwordx4 v[172:175], v253, s[36:37]
	global_load_dwordx4 v[176:179], v253, s[36:37] offset:16
	global_load_dwordx4 v[180:183], v253, s[36:37] offset:512
	global_load_dwordx4 v[188:191], v253, s[36:37] offset:528
	s_waitcnt lgkmcnt(0)
	v_add_f32_e32 v250, v250, v251
	s_and_saveexec_b64 s[28:29], s[2:3]
	global_atomic_add_f32 v149, v250, s[18:19]
	s_mov_b64 exec, s[28:29]
	s_waitcnt vmcnt(19)
	v_pk_add_f32 v[108:109], v[108:109], v[194:195]
	v_pk_add_f32 v[110:111], v[110:111], v[196:197]
	v_pk_add_f32 v[104:105], v[104:105], v[198:199]
	v_pk_add_f32 v[106:107], v[106:107], v[200:201]
	v_pk_add_f32 v[100:101], v[100:101], v[202:203]
	v_pk_add_f32 v[102:103], v[102:103], v[204:205]
	v_pk_add_f32 v[96:97], v[96:97], v[206:207]
	v_pk_add_f32 v[98:99], v[98:99], v[208:209]
	v_add_u32_e32 v253, 0x20000, v148
	global_store_dwordx4 v253, v[108:111], s[72:73]
	global_store_dwordx4 v253, v[104:107], s[72:73] offset:16
	global_store_dwordx4 v253, v[100:103], s[72:73] offset:512
	global_store_dwordx4 v253, v[96:99], s[72:73] offset:528
	v_mul_f32_e32 v250, v108, v108
	v_mul_f32_e32 v251, v109, v109
	v_fmac_f32_e32 v250, v110, v110
	v_fmac_f32_e32 v251, v111, v111
	v_fmac_f32_e32 v250, v104, v104
	v_fmac_f32_e32 v251, v105, v105
	v_fmac_f32_e32 v250, v106, v106
	v_fmac_f32_e32 v251, v107, v107
	v_fmac_f32_e32 v250, v100, v100
	v_fmac_f32_e32 v251, v101, v101
	v_fmac_f32_e32 v250, v102, v102
	v_fmac_f32_e32 v251, v103, v103
	v_fmac_f32_e32 v250, v96, v96
	v_fmac_f32_e32 v251, v97, v97
	v_fmac_f32_e32 v250, v98, v98
	v_fmac_f32_e32 v251, v99, v99
	v_add_f32_e32 v250, v250, v251
	ds_bpermute_b32 v251, v254, v250
	v_pk_mul_f32 v[194:195], v[108:109], v[144:145]
	v_pk_mul_f32 v[196:197], v[110:111], v[146:147]
	v_pk_mul_f32 v[198:199], v[104:105], v[160:161]
	v_pk_mul_f32 v[200:201], v[106:107], v[162:163]
	v_pk_mul_f32 v[202:203], v[100:101], v[164:165]
	v_pk_mul_f32 v[204:205], v[102:103], v[166:167]
	v_pk_mul_f32 v[206:207], v[96:97], v[168:169]
	v_pk_mul_f32 v[208:209], v[98:99], v[170:171]
	v_cvt_pk_bf16_f32 v194, v194, v195
	v_cvt_pk_bf16_f32 v195, v196, v197
	v_cvt_pk_bf16_f32 v196, v198, v199
	v_cvt_pk_bf16_f32 v197, v200, v201
	v_cvt_pk_bf16_f32 v202, v202, v203
	v_cvt_pk_bf16_f32 v203, v204, v205
	v_cvt_pk_bf16_f32 v204, v206, v207
	v_cvt_pk_bf16_f32 v205, v208, v209
	v_lshrrev_b32_e32 v252, 1, v253
	global_store_dwordx4 v252, v[194:197], s[16:17]
	global_store_dwordx4 v252, v[202:205], s[16:17] offset:256
	s_waitcnt lgkmcnt(0)
; #define EPI_FENCE() asm volatile("" ::: "memory")
; __device__ __forceinline__ u32x4 pack8(f32x4 a, f32x4 b) { u32x4 w; w.x = cvt_pk_bf16(a[0], a[1]); w.y = cvt_pk_bf16(a[2], a[3]); w.z = cvt_pk_bf16(b[0], b[1]); w.w = cvt_pk_bf16(b[2], b[3]); return w; }
; __device__ __forceinline__ float dot4(f32x4 a) { return (a[0] * a[0] + a[1] * a[1]) + (a[2] * a[2] + a[3] * a[3]); }
;   __device__ __forceinline__ void operator()(const AccT& acc, const pg8::Unit& u, int wr, int wc, int fr, int fq) const {
;     const int row0 = u.pm * 256 + wr * 64 + fr, col0 = u.pn * 256 + wc * 32 + 8 * fq;
; #pragma unroll
;     for (int ai = 0; ai < 2; ++ai)
; #pragma unroll
;       for (int m = 0; m < 4; ++m) { const int row = row0 + ai * 128 + m * 16; const size_t off = (size_t)row * DM + col0; float s = 0.f;
; #pragma unroll
;         for (int bj = 0; bj < 2; ++bj) { const int co = bj * 128;
;           const f32x4 v0 = *(const f32x4*)(base + off + co) + acc[ai][bj][m][0], v1 = *(const f32x4*)(base + off + co + 4) + acc[ai][bj][m][1];
;           *(f32x4*)(X + off + co) = v0; *(f32x4*)(X + off + co + 4) = v1; s += dot4(v0) + dot4(v1);
;           if (xb) { const f32x4 g0 = *(const f32x4*)(g + col0 + co), g1 = *(const f32x4*)(g + col0 + co + 4); *(u32x4*)(xb + off + co) = pack8(v0 * g0, v1 * g1); } }
;         s += __shfl_xor(s, 16); s += __shfl_xor(s, 32);
;         if (fq == 0) unsafeAtomicAdd(ss + row, s);
;         if (m & 1) EPI_FENCE(); }
;   }
	v_add_f32_e32 v250, v250, v251
	ds_bpermute_b32 v251, v255, v250
	v_add_u32_e32 v252, 0x40, v149
	s_nop 0
	v_add_u32_e32 v253, 0x120000, v148
	global_load_dwordx4 v[194:197], v253, s[36:37]
	global_load_dwordx4 v[198:201], v253, s[36:37] offset:16
	global_load_dwordx4 v[202:205], v253, s[36:37] offset:512
	global_load_dwordx4 v[206:209], v253, s[36:37] offset:528
	s_waitcnt lgkmcnt(0)
	v_add_f32_e32 v250, v250, v251
	s_and_saveexec_b64 s[28:29], s[2:3]
	global_atomic_add_f32 v252, v250, s[18:19]
	s_mov_b64 exec, s[28:29]
	s_waitcnt vmcnt(26)
	v_pk_add_f32 v[92:93], v[92:93], v[210:211]
	v_pk_add_f32 v[94:95], v[94:95], v[212:213]
	v_pk_add_f32 v[88:89], v[88:89], v[214:215]
	v_pk_add_f32 v[90:91], v[90:91], v[216:217]
	v_pk_add_f32 v[84:85], v[84:85], v[218:219]
	v_pk_add_f32 v[86:87], v[86:87], v[220:221]
	v_pk_add_f32 v[80:81], v[80:81], v[222:223]
	v_pk_add_f32 v[82:83], v[82:83], v[224:225]
	v_add_u32_e32 v253, 0x40000, v148
	global_store_dwordx4 v253, v[92:95], s[72:73]
	global_store_dwordx4 v253, v[88:91], s[72:73] offset:16
	global_store_dwordx4 v253, v[84:87], s[72:73] offset:512
	global_store_dwordx4 v253, v[80:83], s[72:73] offset:528
	v_mul_f32_e32 v250, v92, v92
	v_mul_f32_e32 v251, v93, v93
	v_fmac_f32_e32 v250, v94, v94
	v_fmac_f32_e32 v251, v95, v95
	v_fmac_f32_e32 v250, v88, v88
	v_fmac_f32_e32 v251, v89, v89
	v_fmac_f32_e32 v250, v90, v90
	v_fmac_f32_e32 v251, v91, v91
	v_fmac_f32_e32 v250, v84, v84
	v_fmac_f32_e32 v251, v85, v85
	v_fmac_f32_e32 v250, v86, v86
	v_fmac_f32_e32 v251, v87, v87
	v_fmac_f32_e32 v250, v80, v80
	v_fmac_f32_e32 v251, v81, v81
	v_fmac_f32_e32 v250, v82, v82
	v_fmac_f32_e32 v251, v83, v83
	v_add_f32_e32 v250, v250, v251
	ds_bpermute_b32 v251, v254, v250
	v_pk_mul_f32 v[210:211], v[92:93], v[144:145]
	v_pk_mul_f32 v[212:213], v[94:95], v[146:147]
	v_pk_mul_f32 v[214:215], v[88:89], v[160:161]
	v_pk_mul_f32 v[216:217], v[90:91], v[162:163]
	v_pk_mul_f32 v[218:219], v[84:85], v[164:165]
	v_pk_mul_f32 v[220:221], v[86:87], v[166:167]
	v_pk_mul_f32 v[222:223], v[80:81], v[168:169]
	v_pk_mul_f32 v[224:225], v[82:83], v[170:171]
	v_cvt_pk_bf16_f32 v210, v210, v211
	v_cvt_pk_bf16_f32 v211, v212, v213
	v_cvt_pk_bf16_f32 v212, v214, v215
	v_cvt_pk_bf16_f32 v213, v216, v217
	v_cvt_pk_bf16_f32 v218, v218, v219
	v_cvt_pk_bf16_f32 v219, v220, v221
	v_cvt_pk_bf16_f32 v220, v222, v223
	v_cvt_pk_bf16_f32 v221, v224, v225
	v_lshrrev_b32_e32 v252, 1, v253
	global_store_dwordx4 v252, v[210:213], s[16:17]
	global_store_dwordx4 v252, v[218:221], s[16:17] offset:256
	s_waitcnt lgkmcnt(0)
	v_add_f32_e32 v250, v250, v251
	ds_bpermute_b32 v251, v255, v250
	v_add_u32_e32 v252, 0x80, v149
	s_nop 0
	v_add_u32_e32 v253, 0x140000, v148
	global_load_dwordx4 v[210:213], v253, s[36:37]
	global_load_dwordx4 v[214:217], v253, s[36:37] offset:16
	global_load_dwordx4 v[218:221], v253, s[36:37] offset:512
	global_load_dwordx4 v[222:225], v253, s[36:37] offset:528
	s_waitcnt lgkmcnt(0)
	v_add_f32_e32 v250, v250, v251
	s_and_saveexec_b64 s[28:29], s[2:3]
	global_atomic_add_f32 v252, v250, s[18:19]
	s_mov_b64 exec, s[28:29]
	s_waitcnt vmcnt(33)
	v_pk_add_f32 v[76:77], v[76:77], v[234:235]
	v_pk_add_f32 v[78:79], v[78:79], v[236:237]
	v_pk_add_f32 v[72:73], v[72:73], v[238:239]
	v_pk_add_f32 v[74:75], v[74:75], v[240:241]
	v_pk_add_f32 v[68:69], v[68:69], v[242:243]
	v_pk_add_f32 v[70:71], v[70:71], v[244:245]
	v_pk_add_f32 v[64:65], v[64:65], v[246:247]
	v_pk_add_f32 v[66:67], v[66:67], v[248:249]
	v_add_u32_e32 v253, 0x60000, v148
	global_store_dwordx4 v253, v[76:79], s[72:73]
	global_store_dwordx4 v253, v[72:75], s[72:73] offset:16
	global_store_dwordx4 v253, v[68:71], s[72:73] offset:512
	global_store_dwordx4 v253, v[64:67], s[72:73] offset:528
	v_mul_f32_e32 v250, v76, v76
	v_mul_f32_e32 v251, v77, v77
	v_fmac_f32_e32 v250, v78, v78
	v_fmac_f32_e32 v251, v79, v79
	v_fmac_f32_e32 v250, v72, v72
	v_fmac_f32_e32 v251, v73, v73
	v_fmac_f32_e32 v250, v74, v74
	v_fmac_f32_e32 v251, v75, v75
	v_fmac_f32_e32 v250, v68, v68
	v_fmac_f32_e32 v251, v69, v69
	v_fmac_f32_e32 v250, v70, v70
	v_fmac_f32_e32 v251, v71, v71
	v_fmac_f32_e32 v250, v64, v64
	v_fmac_f32_e32 v251, v65, v65
	v_fmac_f32_e32 v250, v66, v66
	v_fmac_f32_e32 v251, v67, v67
	v_add_f32_e32 v250, v250, v251
	ds_bpermute_b32 v251, v254, v250
	v_pk_mul_f32 v[234:235], v[76:77], v[144:145]
	v_pk_mul_f32 v[236:237], v[78:79], v[146:147]
	v_pk_mul_f32 v[238:239], v[72:73], v[160:161]
	v_pk_mul_f32 v[240:241], v[74:75], v[162:163]
	v_pk_mul_f32 v[242:243], v[68:69], v[164:165]
	v_pk_mul_f32 v[244:245], v[70:71], v[166:167]
	v_pk_mul_f32 v[246:247], v[64:65], v[168:169]
	v_pk_mul_f32 v[248:249], v[66:67], v[170:171]
	v_cvt_pk_bf16_f32 v234, v234, v235
	v_cvt_pk_bf16_f32 v235, v236, v237
	v_cvt_pk_bf16_f32 v236, v238, v239
	v_cvt_pk_bf16_f32 v237, v240, v241
	v_cvt_pk_bf16_f32 v242, v242, v243
	v_cvt_pk_bf16_f32 v243, v244, v245
	v_cvt_pk_bf16_f32 v244, v246, v247
	v_cvt_pk_bf16_f32 v245, v248, v249
	v_lshrrev_b32_e32 v252, 1, v253
	global_store_dwordx4 v252, v[234:237], s[16:17]
	global_store_dwordx4 v252, v[242:245], s[16:17] offset:256
	s_waitcnt lgkmcnt(0)
	v_add_f32_e32 v250, v250, v251
	ds_bpermute_b32 v251, v255, v250
	v_add_u32_e32 v252, 0xc0, v149
	s_nop 0
	v_add_u32_e32 v253, 0x160000, v148
	global_load_dwordx4 v[234:237], v253, s[36:37]
	global_load_dwordx4 v[238:241], v253, s[36:37] offset:16
	global_load_dwordx4 v[242:245], v253, s[36:37] offset:512
	global_load_dwordx4 v[246:249], v253, s[36:37] offset:528
	s_waitcnt lgkmcnt(0)
	v_add_f32_e32 v250, v250, v251
	s_and_saveexec_b64 s[28:29], s[2:3]
	global_atomic_add_f32 v252, v250, s[18:19]
	s_mov_b64 exec, s[28:29]
	s_waitcnt vmcnt(34)
; #define EPI_FENCE() asm volatile("" ::: "memory")
; __device__ __forceinline__ u32x4 pack8(f32x4 a, f32x4 b) { u32x4 w; w.x = cvt_pk_bf16(a[0], a[1]); w.y = cvt_pk_bf16(a[2], a[3]); w.z = cvt_pk_bf16(b[0], b[1]); w.w = cvt_pk_bf16(b[2], b[3]); return w; }
; __device__ __forceinline__ float dot4(f32x4 a) { return (a[0] * a[0] + a[1] * a[1]) + (a[2] * a[2] + a[3] * a[3]); }
;   __device__ __forceinline__ void operator()(const AccT& acc, const pg8::Unit& u, int wr, int wc, int fr, int fq) const {
;     const int row0 = u.pm * 256 + wr * 64 + fr, col0 = u.pn * 256 + wc * 32 + 8 * fq;
; #pragma unroll
;     for (int ai = 0; ai < 2; ++ai)
; #pragma unroll
;       for (int m = 0; m < 4; ++m) { const int row = row0 + ai * 128 + m * 16; const size_t off = (size_t)row * DM + col0; float s = 0.f;
; #pragma unroll
;         for (int bj = 0; bj < 2; ++bj) { const int co = bj * 128;
;           const f32x4 v0 = *(const f32x4*)(base + off + co) + acc[ai][bj][m][0], v1 = *(const f32x4*)(base + off + co + 4) + acc[ai][bj][m][1];
;           *(f32x4*)(X + off + co) = v0; *(f32x4*)(X + off + co + 4) = v1; s += dot4(v0) + dot4(v1);
;           if (xb) { const f32x4 g0 = *(const f32x4*)(g + col0 + co), g1 = *(const f32x4*)(g + col0 + co + 4); *(u32x4*)(xb + off + co) = pack8(v0 * g0, v1 * g1); } }
;         s += __shfl_xor(s, 16); s += __shfl_xor(s, 32);
;         if (fq == 0) unsafeAtomicAdd(ss + row, s);
;         if (m & 1) EPI_FENCE(); }
;   }
	v_pk_add_f32 v[60:61], v[60:61], v[172:173]
	v_pk_add_f32 v[62:63], v[62:63], v[174:175]
	v_pk_add_f32 v[56:57], v[56:57], v[176:177]
	v_pk_add_f32 v[58:59], v[58:59], v[178:179]
	v_pk_add_f32 v[52:53], v[52:53], v[180:181]
	v_pk_add_f32 v[54:55], v[54:55], v[182:183]
	v_pk_add_f32 v[48:49], v[48:49], v[188:189]
	v_pk_add_f32 v[50:51], v[50:51], v[190:191]
	v_add_u32_e32 v253, 0x100000, v148
	global_store_dwordx4 v253, v[60:63], s[72:73]
	global_store_dwordx4 v253, v[56:59], s[72:73] offset:16
	global_store_dwordx4 v253, v[52:55], s[72:73] offset:512
	global_store_dwordx4 v253, v[48:51], s[72:73] offset:528
	v_mul_f32_e32 v250, v60, v60
	v_mul_f32_e32 v251, v61, v61
	v_fmac_f32_e32 v250, v62, v62
	v_fmac_f32_e32 v251, v63, v63
	v_fmac_f32_e32 v250, v56, v56
	v_fmac_f32_e32 v251, v57, v57
	v_fmac_f32_e32 v250, v58, v58
	v_fmac_f32_e32 v251, v59, v59
	v_fmac_f32_e32 v250, v52, v52
	v_fmac_f32_e32 v251, v53, v53
	v_fmac_f32_e32 v250, v54, v54
	v_fmac_f32_e32 v251, v55, v55
	v_fmac_f32_e32 v250, v48, v48
	v_fmac_f32_e32 v251, v49, v49
	v_fmac_f32_e32 v250, v50, v50
	v_fmac_f32_e32 v251, v51, v51
	v_add_f32_e32 v250, v250, v251
	ds_bpermute_b32 v251, v254, v250
	v_pk_mul_f32 v[172:173], v[60:61], v[144:145]
	v_pk_mul_f32 v[174:175], v[62:63], v[146:147]
	v_pk_mul_f32 v[176:177], v[56:57], v[160:161]
	v_pk_mul_f32 v[178:179], v[58:59], v[162:163]
	v_pk_mul_f32 v[180:181], v[52:53], v[164:165]
	v_pk_mul_f32 v[182:183], v[54:55], v[166:167]
	v_pk_mul_f32 v[188:189], v[48:49], v[168:169]
	v_pk_mul_f32 v[190:191], v[50:51], v[170:171]
	v_cvt_pk_bf16_f32 v172, v172, v173
	v_cvt_pk_bf16_f32 v173, v174, v175
	v_cvt_pk_bf16_f32 v174, v176, v177
	v_cvt_pk_bf16_f32 v175, v178, v179
	v_cvt_pk_bf16_f32 v180, v180, v181
	v_cvt_pk_bf16_f32 v181, v182, v183
	v_cvt_pk_bf16_f32 v182, v188, v189
	v_cvt_pk_bf16_f32 v183, v190, v191
	v_lshrrev_b32_e32 v252, 1, v253
	global_store_dwordx4 v252, v[172:175], s[16:17]
	global_store_dwordx4 v252, v[180:183], s[16:17] offset:256
	s_waitcnt lgkmcnt(0)
	v_add_f32_e32 v250, v250, v251
	ds_bpermute_b32 v251, v255, v250
	v_add_u32_e32 v252, 0x200, v149
	s_waitcnt lgkmcnt(0)
	v_add_f32_e32 v250, v250, v251
	s_and_saveexec_b64 s[28:29], s[2:3]
	global_atomic_add_f32 v252, v250, s[18:19]
	s_mov_b64 exec, s[28:29]
	s_waitcnt vmcnt(30)
	v_pk_add_f32 v[44:45], v[44:45], v[194:195]
	v_pk_add_f32 v[46:47], v[46:47], v[196:197]
	v_pk_add_f32 v[40:41], v[40:41], v[198:199]
	v_pk_add_f32 v[42:43], v[42:43], v[200:201]
	v_pk_add_f32 v[36:37], v[36:37], v[202:203]
	v_pk_add_f32 v[38:39], v[38:39], v[204:205]
	v_pk_add_f32 v[32:33], v[32:33], v[206:207]
	v_pk_add_f32 v[34:35], v[34:35], v[208:209]
	v_add_u32_e32 v253, 0x120000, v148
	global_store_dwordx4 v253, v[44:47], s[72:73]
	global_store_dwordx4 v253, v[40:43], s[72:73] offset:16
	global_store_dwordx4 v253, v[36:39], s[72:73] offset:512
	global_store_dwordx4 v253, v[32:35], s[72:73] offset:528
	v_mul_f32_e32 v250, v44, v44
	v_mul_f32_e32 v251, v45, v45
	v_fmac_f32_e32 v250, v46, v46
	v_fmac_f32_e32 v251, v47, v47
	v_fmac_f32_e32 v250, v40, v40
	v_fmac_f32_e32 v251, v41, v41
	v_fmac_f32_e32 v250, v42, v42
	v_fmac_f32_e32 v251, v43, v43
	v_fmac_f32_e32 v250, v36, v36
	v_fmac_f32_e32 v251, v37, v37
	v_fmac_f32_e32 v250, v38, v38
	v_fmac_f32_e32 v251, v39, v39
	v_fmac_f32_e32 v250, v32, v32
	v_fmac_f32_e32 v251, v33, v33
	v_fmac_f32_e32 v250, v34, v34
	v_fmac_f32_e32 v251, v35, v35
	v_add_f32_e32 v250, v250, v251
	ds_bpermute_b32 v251, v254, v250
	v_pk_mul_f32 v[194:195], v[44:45], v[144:145]
	v_pk_mul_f32 v[196:197], v[46:47], v[146:147]
	v_pk_mul_f32 v[198:199], v[40:41], v[160:161]
	v_pk_mul_f32 v[200:201], v[42:43], v[162:163]
	v_pk_mul_f32 v[202:203], v[36:37], v[164:165]
	v_pk_mul_f32 v[204:205], v[38:39], v[166:167]
	v_pk_mul_f32 v[206:207], v[32:33], v[168:169]
	v_pk_mul_f32 v[208:209], v[34:35], v[170:171]
	v_cvt_pk_bf16_f32 v194, v194, v195
	v_cvt_pk_bf16_f32 v195, v196, v197
	v_cvt_pk_bf16_f32 v196, v198, v199
	v_cvt_pk_bf16_f32 v197, v200, v201
	v_cvt_pk_bf16_f32 v202, v202, v203
	v_cvt_pk_bf16_f32 v203, v204, v205
	v_cvt_pk_bf16_f32 v204, v206, v207
	v_cvt_pk_bf16_f32 v205, v208, v209
	v_lshrrev_b32_e32 v252, 1, v253
	global_store_dwordx4 v252, v[194:197], s[16:17]
	global_store_dwordx4 v252, v[202:205], s[16:17] offset:256
	s_waitcnt lgkmcnt(0)
	v_add_f32_e32 v250, v250, v251
	ds_bpermute_b32 v251, v255, v250
	v_add_u32_e32 v252, 0x240, v149
	s_waitcnt lgkmcnt(0)
	v_add_f32_e32 v250, v250, v251
	s_and_saveexec_b64 s[28:29], s[2:3]
	global_atomic_add_f32 v252, v250, s[18:19]
	s_mov_b64 exec, s[28:29]
	s_waitcnt vmcnt(26)
; #define EPI_FENCE() asm volatile("" ::: "memory")
; __device__ __forceinline__ u32x4 pack8(f32x4 a, f32x4 b) { u32x4 w; w.x = cvt_pk_bf16(a[0], a[1]); w.y = cvt_pk_bf16(a[2], a[3]); w.z = cvt_pk_bf16(b[0], b[1]); w.w = cvt_pk_bf16(b[2], b[3]); return w; }
; __device__ __forceinline__ float dot4(f32x4 a) { return (a[0] * a[0] + a[1] * a[1]) + (a[2] * a[2] + a[3] * a[3]); }
;   __device__ __forceinline__ void operator()(const AccT& acc, const pg8::Unit& u, int wr, int wc, int fr, int fq) const {
;     const int row0 = u.pm * 256 + wr * 64 + fr, col0 = u.pn * 256 + wc * 32 + 8 * fq;
; #pragma unroll
;     for (int ai = 0; ai < 2; ++ai)
; #pragma unroll
;       for (int m = 0; m < 4; ++m) { const int row = row0 + ai * 128 + m * 16; const size_t off = (size_t)row * DM + col0; float s = 0.f;
; #pragma unroll
;         for (int bj = 0; bj < 2; ++bj) { const int co = bj * 128;
;           const f32x4 v0 = *(const f32x4*)(base + off + co) + acc[ai][bj][m][0], v1 = *(const f32x4*)(base + off + co + 4) + acc[ai][bj][m][1];
;           *(f32x4*)(X + off + co) = v0; *(f32x4*)(X + off + co + 4) = v1; s += dot4(v0) + dot4(v1);
;           if (xb) { const f32x4 g0 = *(const f32x4*)(g + col0 + co), g1 = *(const f32x4*)(g + col0 + co + 4); *(u32x4*)(xb + off + co) = pack8(v0 * g0, v1 * g1); } }
;         s += __shfl_xor(s, 16); s += __shfl_xor(s, 32);
;         if (fq == 0) unsafeAtomicAdd(ss + row, s);
;         if (m & 1) EPI_FENCE(); }
;   }
	v_pk_add_f32 v[28:29], v[28:29], v[210:211]
	v_pk_add_f32 v[30:31], v[30:31], v[212:213]
	v_pk_add_f32 v[24:25], v[24:25], v[214:215]
	v_pk_add_f32 v[26:27], v[26:27], v[216:217]
	v_pk_add_f32 v[20:21], v[20:21], v[218:219]
	v_pk_add_f32 v[22:23], v[22:23], v[220:221]
	v_pk_add_f32 v[16:17], v[16:17], v[222:223]
	v_pk_add_f32 v[18:19], v[18:19], v[224:225]
	v_add_u32_e32 v253, 0x140000, v148
	global_store_dwordx4 v253, v[28:31], s[72:73]
	global_store_dwordx4 v253, v[24:27], s[72:73] offset:16
	global_store_dwordx4 v253, v[20:23], s[72:73] offset:512
	global_store_dwordx4 v253, v[16:19], s[72:73] offset:528
	v_mul_f32_e32 v250, v28, v28
	v_mul_f32_e32 v251, v29, v29
	v_fmac_f32_e32 v250, v30, v30
	v_fmac_f32_e32 v251, v31, v31
	v_fmac_f32_e32 v250, v24, v24
	v_fmac_f32_e32 v251, v25, v25
	v_fmac_f32_e32 v250, v26, v26
	v_fmac_f32_e32 v251, v27, v27
	v_fmac_f32_e32 v250, v20, v20
	v_fmac_f32_e32 v251, v21, v21
	v_fmac_f32_e32 v250, v22, v22
	v_fmac_f32_e32 v251, v23, v23
	v_fmac_f32_e32 v250, v16, v16
	v_fmac_f32_e32 v251, v17, v17
	v_fmac_f32_e32 v250, v18, v18
	v_fmac_f32_e32 v251, v19, v19
	v_add_f32_e32 v250, v250, v251
	ds_bpermute_b32 v251, v254, v250
	v_pk_mul_f32 v[210:211], v[28:29], v[144:145]
	v_pk_mul_f32 v[212:213], v[30:31], v[146:147]
	v_pk_mul_f32 v[214:215], v[24:25], v[160:161]
	v_pk_mul_f32 v[216:217], v[26:27], v[162:163]
	v_pk_mul_f32 v[218:219], v[20:21], v[164:165]
	v_pk_mul_f32 v[220:221], v[22:23], v[166:167]
	v_pk_mul_f32 v[222:223], v[16:17], v[168:169]
	v_pk_mul_f32 v[224:225], v[18:19], v[170:171]
	v_cvt_pk_bf16_f32 v210, v210, v211
	v_cvt_pk_bf16_f32 v211, v212, v213
	v_cvt_pk_bf16_f32 v212, v214, v215
	v_cvt_pk_bf16_f32 v213, v216, v217
	v_cvt_pk_bf16_f32 v218, v218, v219
	v_cvt_pk_bf16_f32 v219, v220, v221
	v_cvt_pk_bf16_f32 v220, v222, v223
	v_cvt_pk_bf16_f32 v221, v224, v225
	v_lshrrev_b32_e32 v252, 1, v253
	global_store_dwordx4 v252, v[210:213], s[16:17]
	global_store_dwordx4 v252, v[218:221], s[16:17] offset:256
	s_waitcnt lgkmcnt(0)
	v_add_f32_e32 v250, v250, v251
	ds_bpermute_b32 v251, v255, v250
	v_add_u32_e32 v252, 0x280, v149
	s_waitcnt lgkmcnt(0)
	v_add_f32_e32 v250, v250, v251
	s_and_saveexec_b64 s[28:29], s[2:3]
	global_atomic_add_f32 v252, v250, s[18:19]
	s_mov_b64 exec, s[28:29]
	s_waitcnt vmcnt(22)
	v_pk_add_f32 v[12:13], v[12:13], v[234:235]
	v_pk_add_f32 v[14:15], v[14:15], v[236:237]
	v_pk_add_f32 v[8:9], v[8:9], v[238:239]
	v_pk_add_f32 v[10:11], v[10:11], v[240:241]
	v_pk_add_f32 v[4:5], v[4:5], v[242:243]
	v_pk_add_f32 v[6:7], v[6:7], v[244:245]
	v_pk_add_f32 v[0:1], v[0:1], v[246:247]
	v_pk_add_f32 v[2:3], v[2:3], v[248:249]
	v_add_u32_e32 v253, 0x160000, v148
	global_store_dwordx4 v253, v[12:15], s[72:73]
	global_store_dwordx4 v253, v[8:11], s[72:73] offset:16
	global_store_dwordx4 v253, v[4:7], s[72:73] offset:512
	global_store_dwordx4 v253, v[0:3], s[72:73] offset:528
	v_mul_f32_e32 v250, v12, v12
	v_mul_f32_e32 v251, v13, v13
	v_fmac_f32_e32 v250, v14, v14
	v_fmac_f32_e32 v251, v15, v15
	v_fmac_f32_e32 v250, v8, v8
	v_fmac_f32_e32 v251, v9, v9
	v_fmac_f32_e32 v250, v10, v10
	v_fmac_f32_e32 v251, v11, v11
	v_fmac_f32_e32 v250, v4, v4
	v_fmac_f32_e32 v251, v5, v5
	v_fmac_f32_e32 v250, v6, v6
	v_fmac_f32_e32 v251, v7, v7
	v_fmac_f32_e32 v250, v0, v0
	v_fmac_f32_e32 v251, v1, v1
	v_fmac_f32_e32 v250, v2, v2
	v_fmac_f32_e32 v251, v3, v3
	v_add_f32_e32 v250, v250, v251
	ds_bpermute_b32 v251, v254, v250
	v_pk_mul_f32 v[234:235], v[12:13], v[144:145]
	v_pk_mul_f32 v[236:237], v[14:15], v[146:147]
	v_pk_mul_f32 v[238:239], v[8:9], v[160:161]
	v_pk_mul_f32 v[240:241], v[10:11], v[162:163]
	v_pk_mul_f32 v[242:243], v[4:5], v[164:165]
	v_pk_mul_f32 v[244:245], v[6:7], v[166:167]
	v_pk_mul_f32 v[246:247], v[0:1], v[168:169]
	v_pk_mul_f32 v[248:249], v[2:3], v[170:171]
	v_cvt_pk_bf16_f32 v234, v234, v235
	v_cvt_pk_bf16_f32 v235, v236, v237
	v_cvt_pk_bf16_f32 v236, v238, v239
	v_cvt_pk_bf16_f32 v237, v240, v241
	v_cvt_pk_bf16_f32 v242, v242, v243
	v_cvt_pk_bf16_f32 v243, v244, v245
	v_cvt_pk_bf16_f32 v244, v246, v247
	v_cvt_pk_bf16_f32 v245, v248, v249
	v_lshrrev_b32_e32 v252, 1, v253
	global_store_dwordx4 v252, v[234:237], s[16:17]
	global_store_dwordx4 v252, v[242:245], s[16:17] offset:256
	s_waitcnt lgkmcnt(0)
	v_add_f32_e32 v250, v250, v251
	ds_bpermute_b32 v251, v255, v250
	v_add_u32_e32 v252, 0x2c0, v149
	s_waitcnt lgkmcnt(0)
	v_add_f32_e32 v250, v250, v251
	s_and_saveexec_b64 s[28:29], s[2:3]
	global_atomic_add_f32 v252, v250, s[18:19]
	s_mov_b64 exec, s[28:29]
	s_branch .LBB0_502

; __global__ void __launch_bounds__(512, 2) fwd_megakernel(const Params p) {
	.amdhsa_kernel _Z14fwd_megakernel6Params
		.amdhsa_group_segment_fixed_size 0
		.amdhsa_private_segment_fixed_size 0
		.amdhsa_kernarg_size 488
		.amdhsa_user_sgpr_count 2
		.amdhsa_user_sgpr_dispatch_ptr 0
		.amdhsa_user_sgpr_queue_ptr 0
		.amdhsa_user_sgpr_kernarg_segment_ptr 1
		.amdhsa_user_sgpr_dispatch_id 0
		.amdhsa_user_sgpr_kernarg_preload_length 0
		.amdhsa_user_sgpr_kernarg_preload_offset 0
		.amdhsa_user_sgpr_private_segment_size 0
		.amdhsa_uses_dynamic_stack 0
		.amdhsa_enable_private_segment 0
		.amdhsa_system_sgpr_workgroup_id_x 1
		.amdhsa_system_sgpr_workgroup_id_y 0
		.amdhsa_system_sgpr_workgroup_id_z 0
		.amdhsa_system_sgpr_workgroup_info 0
		.amdhsa_system_vgpr_workitem_id 2
		.amdhsa_next_free_vgpr 256
		.amdhsa_next_free_sgpr 98
		.amdhsa_accum_offset 256
		.amdhsa_reserve_vcc 1
		.amdhsa_float_round_mode_32 0
		.amdhsa_float_round_mode_16_64 0
		.amdhsa_float_denorm_mode_32 3
		.amdhsa_float_denorm_mode_16_64 3
		.amdhsa_dx10_clamp 1
		.amdhsa_ieee_mode 1
		.amdhsa_fp16_overflow 0
		.amdhsa_tg_split 0
		.amdhsa_exception_fp_ieee_invalid_op 0
		.amdhsa_exception_fp_denorm_src 0
		.amdhsa_exception_fp_ieee_div_zero 0
		.amdhsa_exception_fp_ieee_overflow 0
		.amdhsa_exception_fp_ieee_underflow 0
		.amdhsa_exception_fp_ieee_inexact 0
		.amdhsa_exception_int_div_zero 0
	.end_amdhsa_kernel

; __global__ void __launch_bounds__(512, 2) fwd_megakernel(const Params p) {
amdhsa.kernels:
  - .agpr_count:     0
    .args:
      - .offset:         0
        .size:           232
        .value_kind:     by_value
      - .offset:         232
        .size:           4
        .value_kind:     hidden_block_count_x
      - .offset:         236
        .size:           4
        .value_kind:     hidden_block_count_y
      - .offset:         240
        .size:           4
        .value_kind:     hidden_block_count_z
      - .offset:         244
        .size:           2
        .value_kind:     hidden_group_size_x
      - .offset:         246
        .size:           2
        .value_kind:     hidden_group_size_y
      - .offset:         248
        .size:           2
        .value_kind:     hidden_group_size_z
      - .offset:         250
        .size:           2
        .value_kind:     hidden_remainder_x
      - .offset:         252
        .size:           2
        .value_kind:     hidden_remainder_y
      - .offset:         254
        .size:           2
        .value_kind:     hidden_remainder_z
      - .offset:         272
        .size:           8
        .value_kind:     hidden_global_offset_x
      - .offset:         280
        .size:           8
        .value_kind:     hidden_global_offset_y
      - .offset:         288
        .size:           8
        .value_kind:     hidden_global_offset_z
      - .offset:         296
        .size:           2
        .value_kind:     hidden_grid_dims
      - .offset:         320
        .size:           8
        .value_kind:     hidden_multigrid_sync_arg
      - .offset:         352
        .size:           4
        .value_kind:     hidden_dynamic_lds_size
    .group_segment_fixed_size: 0
    .kernarg_segment_align: 8
    .kernarg_segment_size: 488
    .language:       OpenCL C
    .language_version:
      - 2
      - 0
    .max_flat_workgroup_size: 512
    .name:           _Z14fwd_megakernel6Params
    .private_segment_fixed_size: 0
    .sgpr_count:     104
    .sgpr_spill_count: 1
    .symbol:         _Z14fwd_megakernel6Params.kd
    .uniform_work_group_size: 1
    .uses_dynamic_stack: false
    .vgpr_count:     256
    .vgpr_spill_count: 0
    .wavefront_size: 64
